# non-temporal (nt) cache policy on the cache_convert fast paths' once-read f32 loads and once-written stores
# speedup vs baseline: 1.0125x; 1.0092x over previous
; __device__ __forceinline__ void cache_convert(const Params& P, int l, int pct0, int pct1, int part, int nparts) {
;     int tid = threadIdx.x; asm volatile("" : "+v"(tid));
;     constexpr unsigned NGL = 32u * 512u * 512u / 8u;
;     const unsigned g0 = (unsigned)((unsigned long long)(2u * NGL) * pct0 / 100u), g1 = (unsigned)((unsigned long long)(2u * NGL) * pct1 / 100u);
;     const float* ck = P.in[3] + (size_t)l * 32 * 512 * 512; const float* cv = P.in[4] + (size_t)l * 32 * 512 * 512;
;     bf16_t* kb = (bf16_t*)(P.ws + WS_KB16) + (size_t)l * 32 * 512 * 512; bf16_t* vb = (bf16_t*)(P.ws + WS_VB16) + (size_t)l * 32 * 512 * 512;
;     float* ok = P.out + OFF_KS + (size_t)l * 32 * 512 * 512; float* ov = P.out + OFF_VS + (size_t)l * 32 * 512 * 512;
; #pragma unroll 8
;     for (unsigned gi = g0 + (unsigned)part * 512u + tid; gi < g1; gi += (unsigned)nparts * 512u) {
;         const bool isv = gi >= NGL; const unsigned e = (isv ? gi - NGL : gi) * 8u; const int key = (int)((e >> 9) & 511u);
;         const float* src = (isv ? cv : ck) + e;
;         const f32x4 k0 = *(const f32x4*)src, k1 = *(const f32x4*)(src + 4);
;         *(bf16x8*)((isv ? vb : kb) + e) = pack8v(k0, k1);
;         if (key >= 16) { float* d = (isv ? ov : ok) + e - 16 * 512; *(f32x4*)d = k0; *(f32x4*)(d + 4) = k1; }
;     }
.LBB0_679:
	v_readlane_b32 s16, v10, 63
	s_mul_i32 s17, s13, 7
	s_add_u32 s16, s16, s17
	s_cmp_lt_u32 s16, s12
	s_cbranch_scc0 .Lcc_try4
	v_readlane_b32 s22, v253, 61
	v_readlane_b32 s23, v253, 62
	v_readlane_b32 s24, v253, 63
	v_readlane_b32 s25, v254, 0
	s_mov_b64 s[18:19], s[22:23]
	s_mov_b64 s[20:21], s[24:25]
	s_mov_b32 s0, 0xfffff
	s_mov_b32 s16, 0
	v_and_b32_e32 v2, 63, v208
	v_add_u32_e32 v3, 1, v2
	v_lshrrev_b32_e32 v3, 1, v3
	v_and_b32_e32 v2, 1, v2
	v_sub_u32_e32 v9, v10, v3
	v_lshlrev_b32_e32 v19, 2, v2
	v_mov_b32_e32 v105, 0
	v_mov_b32_e32 v107, 0
	v_mov_b32_e32 v109, 0
	v_mov_b32_e32 v111, 0
	v_mov_b32_e32 v113, 0
	v_mov_b32_e32 v115, 0
	v_mov_b32_e32 v117, 0
	v_mov_b32_e32 v119, 0
	v_mov_b32_e32 v121, 0
	v_mov_b32_e32 v123, 0
	v_mov_b32_e32 v125, 0
	v_mov_b32_e32 v127, 0
	v_mov_b32_e32 v129, 0
	v_mov_b32_e32 v131, 0
	v_mov_b32_e32 v133, 0
	v_mov_b32_e32 v135, 0
	v_add3_u32 v2, v9, s16, 0
	s_nop 0
	v_cmp_lt_u32_e32 vcc, s0, v2
	v_lshl_add_u32 v3, v2, 3, v19
	v_mov_b32_e32 v5, s19
	v_add_u32_e32 v4, 0xff800000, v3
	v_mov_b32_e32 v6, s21
	v_cndmask_b32_e32 v104, v3, v4, vcc
	v_cndmask_b32_e32 v7, v5, v6, vcc
	v_mov_b32_e32 v5, s18
	v_mov_b32_e32 v8, s20
	v_cndmask_b32_e32 v6, v5, v8, vcc
	v_lshl_add_u64 v[6:7], v[6:7], 0, s[62:63]
	v_lshl_add_u64 v[6:7], v[104:105], 2, v[6:7]
	global_load_dwordx4 v[20:23], v[6:7], off nt
	v_add3_u32 v2, v9, s16, 32
	s_nop 0
	v_cmp_lt_u32_e32 vcc, s0, v2
	v_lshl_add_u32 v3, v2, 3, v19
	v_mov_b32_e32 v5, s19
	v_add_u32_e32 v4, 0xff800000, v3
	v_mov_b32_e32 v6, s21
	v_cndmask_b32_e32 v106, v3, v4, vcc
	v_cndmask_b32_e32 v7, v5, v6, vcc
	v_mov_b32_e32 v5, s18
	v_mov_b32_e32 v8, s20
	v_cndmask_b32_e32 v6, v5, v8, vcc
	v_lshl_add_u64 v[6:7], v[6:7], 0, s[62:63]
	v_lshl_add_u64 v[6:7], v[106:107], 2, v[6:7]
	global_load_dwordx4 v[24:27], v[6:7], off nt
	s_add_u32 s16, s16, s13
	v_add3_u32 v2, v9, s16, 0
	s_nop 0
	v_cmp_lt_u32_e32 vcc, s0, v2
	v_lshl_add_u32 v3, v2, 3, v19
	v_mov_b32_e32 v5, s19
	v_add_u32_e32 v4, 0xff800000, v3
	v_mov_b32_e32 v6, s21
	v_cndmask_b32_e32 v108, v3, v4, vcc
	v_cndmask_b32_e32 v7, v5, v6, vcc
	v_mov_b32_e32 v5, s18
	v_mov_b32_e32 v8, s20
	v_cndmask_b32_e32 v6, v5, v8, vcc
	v_lshl_add_u64 v[6:7], v[6:7], 0, s[62:63]
	v_lshl_add_u64 v[6:7], v[108:109], 2, v[6:7]
	global_load_dwordx4 v[28:31], v[6:7], off nt
	v_add3_u32 v2, v9, s16, 32
	s_nop 0
	v_cmp_lt_u32_e32 vcc, s0, v2
	v_lshl_add_u32 v3, v2, 3, v19
	v_mov_b32_e32 v5, s19
	v_add_u32_e32 v4, 0xff800000, v3
	v_mov_b32_e32 v6, s21
	v_cndmask_b32_e32 v110, v3, v4, vcc
	v_cndmask_b32_e32 v7, v5, v6, vcc
	v_mov_b32_e32 v5, s18
	v_mov_b32_e32 v8, s20
	v_cndmask_b32_e32 v6, v5, v8, vcc
	v_lshl_add_u64 v[6:7], v[6:7], 0, s[62:63]
	v_lshl_add_u64 v[6:7], v[110:111], 2, v[6:7]
	global_load_dwordx4 v[32:35], v[6:7], off nt
	s_add_u32 s16, s16, s13
	v_add3_u32 v2, v9, s16, 0
	s_nop 0
	v_cmp_lt_u32_e32 vcc, s0, v2
	v_lshl_add_u32 v3, v2, 3, v19
	v_mov_b32_e32 v5, s19
	v_add_u32_e32 v4, 0xff800000, v3
	v_mov_b32_e32 v6, s21
	v_cndmask_b32_e32 v112, v3, v4, vcc
	v_cndmask_b32_e32 v7, v5, v6, vcc
	v_mov_b32_e32 v5, s18
	v_mov_b32_e32 v8, s20
	v_cndmask_b32_e32 v6, v5, v8, vcc
	v_lshl_add_u64 v[6:7], v[6:7], 0, s[62:63]
	v_lshl_add_u64 v[6:7], v[112:113], 2, v[6:7]
	global_load_dwordx4 v[36:39], v[6:7], off nt
	v_add3_u32 v2, v9, s16, 32
	s_nop 0
	v_cmp_lt_u32_e32 vcc, s0, v2
	v_lshl_add_u32 v3, v2, 3, v19
	v_mov_b32_e32 v5, s19
	v_add_u32_e32 v4, 0xff800000, v3
	v_mov_b32_e32 v6, s21
	v_cndmask_b32_e32 v114, v3, v4, vcc
	v_cndmask_b32_e32 v7, v5, v6, vcc
	v_mov_b32_e32 v5, s18
	v_mov_b32_e32 v8, s20
	v_cndmask_b32_e32 v6, v5, v8, vcc
	v_lshl_add_u64 v[6:7], v[6:7], 0, s[62:63]
	v_lshl_add_u64 v[6:7], v[114:115], 2, v[6:7]
	global_load_dwordx4 v[40:43], v[6:7], off nt
	s_add_u32 s16, s16, s13
	v_add3_u32 v2, v9, s16, 0
	s_nop 0
	v_cmp_lt_u32_e32 vcc, s0, v2
	v_lshl_add_u32 v3, v2, 3, v19
	v_mov_b32_e32 v5, s19
	v_add_u32_e32 v4, 0xff800000, v3
	v_mov_b32_e32 v6, s21
	v_cndmask_b32_e32 v116, v3, v4, vcc
	v_cndmask_b32_e32 v7, v5, v6, vcc
	v_mov_b32_e32 v5, s18
	v_mov_b32_e32 v8, s20
	v_cndmask_b32_e32 v6, v5, v8, vcc
	v_lshl_add_u64 v[6:7], v[6:7], 0, s[62:63]
	v_lshl_add_u64 v[6:7], v[116:117], 2, v[6:7]
	global_load_dwordx4 v[44:47], v[6:7], off nt
	v_add3_u32 v2, v9, s16, 32
	s_nop 0
	v_cmp_lt_u32_e32 vcc, s0, v2
	v_lshl_add_u32 v3, v2, 3, v19
	v_mov_b32_e32 v5, s19
	v_add_u32_e32 v4, 0xff800000, v3
	v_mov_b32_e32 v6, s21
	v_cndmask_b32_e32 v118, v3, v4, vcc
	v_cndmask_b32_e32 v7, v5, v6, vcc
	v_mov_b32_e32 v5, s18
	v_mov_b32_e32 v8, s20
	v_cndmask_b32_e32 v6, v5, v8, vcc
	v_lshl_add_u64 v[6:7], v[6:7], 0, s[62:63]
	v_lshl_add_u64 v[6:7], v[118:119], 2, v[6:7]
	global_load_dwordx4 v[48:51], v[6:7], off nt
	s_add_u32 s16, s16, s13
	v_add3_u32 v2, v9, s16, 0
	s_nop 0
	v_cmp_lt_u32_e32 vcc, s0, v2
	v_lshl_add_u32 v3, v2, 3, v19
	v_mov_b32_e32 v5, s19
	v_add_u32_e32 v4, 0xff800000, v3
	v_mov_b32_e32 v6, s21
	v_cndmask_b32_e32 v120, v3, v4, vcc
	v_cndmask_b32_e32 v7, v5, v6, vcc
	v_mov_b32_e32 v5, s18
	v_mov_b32_e32 v8, s20
	v_cndmask_b32_e32 v6, v5, v8, vcc
	v_lshl_add_u64 v[6:7], v[6:7], 0, s[62:63]
	v_lshl_add_u64 v[6:7], v[120:121], 2, v[6:7]
	global_load_dwordx4 v[52:55], v[6:7], off nt
	v_add3_u32 v2, v9, s16, 32
	s_nop 0
	v_cmp_lt_u32_e32 vcc, s0, v2
	v_lshl_add_u32 v3, v2, 3, v19
	v_mov_b32_e32 v5, s19
	v_add_u32_e32 v4, 0xff800000, v3
	v_mov_b32_e32 v6, s21
	v_cndmask_b32_e32 v122, v3, v4, vcc
	v_cndmask_b32_e32 v7, v5, v6, vcc
	v_mov_b32_e32 v5, s18
	v_mov_b32_e32 v8, s20
	v_cndmask_b32_e32 v6, v5, v8, vcc
	v_lshl_add_u64 v[6:7], v[6:7], 0, s[62:63]
	v_lshl_add_u64 v[6:7], v[122:123], 2, v[6:7]
	global_load_dwordx4 v[56:59], v[6:7], off nt
; __device__ __forceinline__ void cache_convert(const Params& P, int l, int pct0, int pct1, int part, int nparts) {
;     ...
;     for (unsigned gi = g0 + (unsigned)part * 512u + tid; gi < g1; gi += (unsigned)nparts * 512u) {
;         const bool isv = gi >= NGL; const unsigned e = (isv ? gi - NGL : gi) * 8u; const int key = (int)((e >> 9) & 511u);
;         const float* src = (isv ? cv : ck) + e;
;         const f32x4 k0 = *(const f32x4*)src, k1 = *(const f32x4*)(src + 4);
;         *(bf16x8*)((isv ? vb : kb) + e) = pack8v(k0, k1);
;         if (key >= 16) { float* d = (isv ? ov : ok) + e - 16 * 512; *(f32x4*)d = k0; *(f32x4*)(d + 4) = k1; }
	s_add_u32 s16, s16, s13
	v_add3_u32 v2, v9, s16, 0
	s_nop 0
	v_cmp_lt_u32_e32 vcc, s0, v2
	v_lshl_add_u32 v3, v2, 3, v19
	v_mov_b32_e32 v5, s19
	v_add_u32_e32 v4, 0xff800000, v3
	v_mov_b32_e32 v6, s21
	v_cndmask_b32_e32 v124, v3, v4, vcc
	v_cndmask_b32_e32 v7, v5, v6, vcc
	v_mov_b32_e32 v5, s18
	v_mov_b32_e32 v8, s20
	v_cndmask_b32_e32 v6, v5, v8, vcc
	v_lshl_add_u64 v[6:7], v[6:7], 0, s[62:63]
	v_lshl_add_u64 v[6:7], v[124:125], 2, v[6:7]
	global_load_dwordx4 v[60:63], v[6:7], off nt
	v_add3_u32 v2, v9, s16, 32
	s_nop 0
	v_cmp_lt_u32_e32 vcc, s0, v2
	v_lshl_add_u32 v3, v2, 3, v19
	v_mov_b32_e32 v5, s19
	v_add_u32_e32 v4, 0xff800000, v3
	v_mov_b32_e32 v6, s21
	v_cndmask_b32_e32 v126, v3, v4, vcc
	v_cndmask_b32_e32 v7, v5, v6, vcc
	v_mov_b32_e32 v5, s18
	v_mov_b32_e32 v8, s20
	v_cndmask_b32_e32 v6, v5, v8, vcc
	v_lshl_add_u64 v[6:7], v[6:7], 0, s[62:63]
	v_lshl_add_u64 v[6:7], v[126:127], 2, v[6:7]
	global_load_dwordx4 v[64:67], v[6:7], off nt
	s_add_u32 s16, s16, s13
	v_add3_u32 v2, v9, s16, 0
	s_nop 0
	v_cmp_lt_u32_e32 vcc, s0, v2
	v_lshl_add_u32 v3, v2, 3, v19
	v_mov_b32_e32 v5, s19
	v_add_u32_e32 v4, 0xff800000, v3
	v_mov_b32_e32 v6, s21
	v_cndmask_b32_e32 v128, v3, v4, vcc
	v_cndmask_b32_e32 v7, v5, v6, vcc
	v_mov_b32_e32 v5, s18
	v_mov_b32_e32 v8, s20
	v_cndmask_b32_e32 v6, v5, v8, vcc
	v_lshl_add_u64 v[6:7], v[6:7], 0, s[62:63]
	v_lshl_add_u64 v[6:7], v[128:129], 2, v[6:7]
	global_load_dwordx4 v[68:71], v[6:7], off nt
	v_add3_u32 v2, v9, s16, 32
	s_nop 0
	v_cmp_lt_u32_e32 vcc, s0, v2
	v_lshl_add_u32 v3, v2, 3, v19
	v_mov_b32_e32 v5, s19
	v_add_u32_e32 v4, 0xff800000, v3
	v_mov_b32_e32 v6, s21
	v_cndmask_b32_e32 v130, v3, v4, vcc
	v_cndmask_b32_e32 v7, v5, v6, vcc
	v_mov_b32_e32 v5, s18
	v_mov_b32_e32 v8, s20
	v_cndmask_b32_e32 v6, v5, v8, vcc
	v_lshl_add_u64 v[6:7], v[6:7], 0, s[62:63]
	v_lshl_add_u64 v[6:7], v[130:131], 2, v[6:7]
	global_load_dwordx4 v[72:75], v[6:7], off nt
	s_add_u32 s16, s16, s13
	v_add3_u32 v2, v9, s16, 0
	s_nop 0
	v_cmp_lt_u32_e32 vcc, s0, v2
	v_lshl_add_u32 v3, v2, 3, v19
	v_mov_b32_e32 v5, s19
	v_add_u32_e32 v4, 0xff800000, v3
	v_mov_b32_e32 v6, s21
	v_cndmask_b32_e32 v132, v3, v4, vcc
	v_cndmask_b32_e32 v7, v5, v6, vcc
	v_mov_b32_e32 v5, s18
	v_mov_b32_e32 v8, s20
	v_cndmask_b32_e32 v6, v5, v8, vcc
	v_lshl_add_u64 v[6:7], v[6:7], 0, s[62:63]
	v_lshl_add_u64 v[6:7], v[132:133], 2, v[6:7]
	global_load_dwordx4 v[76:79], v[6:7], off nt
	v_add3_u32 v2, v9, s16, 32
	s_nop 0
	v_cmp_lt_u32_e32 vcc, s0, v2
	v_lshl_add_u32 v3, v2, 3, v19
	v_mov_b32_e32 v5, s19
	v_add_u32_e32 v4, 0xff800000, v3
	v_mov_b32_e32 v6, s21
	v_cndmask_b32_e32 v134, v3, v4, vcc
	v_cndmask_b32_e32 v7, v5, v6, vcc
	v_mov_b32_e32 v5, s18
	v_mov_b32_e32 v8, s20
	v_cndmask_b32_e32 v6, v5, v8, vcc
	v_lshl_add_u64 v[6:7], v[6:7], 0, s[62:63]
	v_lshl_add_u64 v[6:7], v[134:135], 2, v[6:7]
	global_load_dwordx4 v[80:83], v[6:7], off nt
	s_mov_b32 s16, 0
	v_add3_u32 v2, v9, s16, 0
	s_mov_b32 s0, 0xfffff
	v_mov_b32_e32 v4, 0x24300000
	v_cmp_lt_u32_e32 vcc, s0, v2
	v_mov_b32_e32 v5, 0x28300000
	v_mov_b32_e32 v17, v1
	v_and_b32_e32 v18, 0x3e000, v104
	v_cndmask_b32_e32 v16, v4, v5, vcc
	v_cmp_ne_u32_e64 s[0:1], 0, v18
	v_lshl_add_u64 v[16:17], s[4:5], 0, v[16:17]
	v_lshl_add_u64 v[16:17], v[104:105], 1, v[16:17]
	s_waitcnt vmcnt(15)
	v_cvt_pk_bf16_f32 v12, v20, v21
	v_cvt_pk_bf16_f32 v13, v22, v23
	s_nop 0
	global_store_dwordx2 v[16:17], v[12:13], off nt
	s_and_saveexec_b64 s[10:11], s[0:1]
	s_cbranch_execz .Lcc_skip_u8_0
	v_mov_b32_e32 v4, 0x6222000
	v_mov_b32_e32 v5, 0xe222000
	v_cndmask_b32_e32 v4, v4, v5, vcc
	v_mov_b32_e32 v5, v1
	v_lshl_add_u64 v[4:5], s[6:7], 0, v[4:5]
	v_lshl_add_u64 v[4:5], v[104:105], 2, v[4:5]
	v_add_co_u32_e32 v4, vcc, 0xffff8000, v4
	s_nop 1
	v_addc_co_u32_e32 v5, vcc, -1, v5, vcc
	s_nop 0
	global_store_dwordx4 v[4:5], v[20:23], off nt
.Lcc_skip_u8_0:
	s_or_b64 exec, exec, s[10:11]
	v_add3_u32 v2, v9, s16, 32
	s_mov_b32 s0, 0xfffff
	v_mov_b32_e32 v4, 0x24300000
	v_cmp_lt_u32_e32 vcc, s0, v2
	v_mov_b32_e32 v5, 0x28300000
	v_mov_b32_e32 v17, v1
	v_and_b32_e32 v18, 0x3e000, v106
	v_cndmask_b32_e32 v16, v4, v5, vcc
	v_cmp_ne_u32_e64 s[0:1], 0, v18
	v_lshl_add_u64 v[16:17], s[4:5], 0, v[16:17]
	v_lshl_add_u64 v[16:17], v[106:107], 1, v[16:17]
	s_waitcnt vmcnt(15)
	v_cvt_pk_bf16_f32 v14, v24, v25
	v_cvt_pk_bf16_f32 v15, v26, v27
	s_nop 0
	global_store_dwordx2 v[16:17], v[14:15], off nt
	s_and_saveexec_b64 s[10:11], s[0:1]
	s_cbranch_execz .Lcc_skip_u8_1
	v_mov_b32_e32 v4, 0x6222000
	v_mov_b32_e32 v5, 0xe222000
	v_cndmask_b32_e32 v4, v4, v5, vcc
	v_mov_b32_e32 v5, v1
	v_lshl_add_u64 v[4:5], s[6:7], 0, v[4:5]
	v_lshl_add_u64 v[4:5], v[106:107], 2, v[4:5]
	v_add_co_u32_e32 v4, vcc, 0xffff8000, v4
	s_nop 1
	v_addc_co_u32_e32 v5, vcc, -1, v5, vcc
	s_nop 0
	global_store_dwordx4 v[4:5], v[24:27], off nt
.Lcc_skip_u8_1:
	s_or_b64 exec, exec, s[10:11]
	s_add_u32 s16, s16, s13
	v_add3_u32 v2, v9, s16, 0
	s_mov_b32 s0, 0xfffff
	v_mov_b32_e32 v4, 0x24300000
	v_cmp_lt_u32_e32 vcc, s0, v2
	v_mov_b32_e32 v5, 0x28300000
	v_mov_b32_e32 v17, v1
	v_and_b32_e32 v18, 0x3e000, v108
	v_cndmask_b32_e32 v16, v4, v5, vcc
	v_cmp_ne_u32_e64 s[0:1], 0, v18
	v_lshl_add_u64 v[16:17], s[4:5], 0, v[16:17]
	v_lshl_add_u64 v[16:17], v[108:109], 1, v[16:17]
	s_waitcnt vmcnt(15)
	v_cvt_pk_bf16_f32 v100, v28, v29
	v_cvt_pk_bf16_f32 v101, v30, v31
	s_nop 0
	global_store_dwordx2 v[16:17], v[100:101], off nt
	s_and_saveexec_b64 s[10:11], s[0:1]
	s_cbranch_execz .Lcc_skip_u8_2
	v_mov_b32_e32 v4, 0x6222000
	v_mov_b32_e32 v5, 0xe222000
	v_cndmask_b32_e32 v4, v4, v5, vcc
	v_mov_b32_e32 v5, v1
	v_lshl_add_u64 v[4:5], s[6:7], 0, v[4:5]
	v_lshl_add_u64 v[4:5], v[108:109], 2, v[4:5]
	v_add_co_u32_e32 v4, vcc, 0xffff8000, v4
	s_nop 1
	v_addc_co_u32_e32 v5, vcc, -1, v5, vcc
	s_nop 0
	global_store_dwordx4 v[4:5], v[28:31], off nt
; __device__ __forceinline__ void cache_convert(const Params& P, int l, int pct0, int pct1, int part, int nparts) {
;     ...
;     for (unsigned gi = g0 + (unsigned)part * 512u + tid; gi < g1; gi += (unsigned)nparts * 512u) {
;         const bool isv = gi >= NGL; const unsigned e = (isv ? gi - NGL : gi) * 8u; const int key = (int)((e >> 9) & 511u);
;         const float* src = (isv ? cv : ck) + e;
;         const f32x4 k0 = *(const f32x4*)src, k1 = *(const f32x4*)(src + 4);
;         *(bf16x8*)((isv ? vb : kb) + e) = pack8v(k0, k1);
;         if (key >= 16) { float* d = (isv ? ov : ok) + e - 16 * 512; *(f32x4*)d = k0; *(f32x4*)(d + 4) = k1; }
.Lcc_skip_u8_2:
	s_or_b64 exec, exec, s[10:11]
	v_add3_u32 v2, v9, s16, 32
	s_mov_b32 s0, 0xfffff
	v_mov_b32_e32 v4, 0x24300000
	v_cmp_lt_u32_e32 vcc, s0, v2
	v_mov_b32_e32 v5, 0x28300000
	v_mov_b32_e32 v17, v1
	v_and_b32_e32 v18, 0x3e000, v110
	v_cndmask_b32_e32 v16, v4, v5, vcc
	v_cmp_ne_u32_e64 s[0:1], 0, v18
	v_lshl_add_u64 v[16:17], s[4:5], 0, v[16:17]
	v_lshl_add_u64 v[16:17], v[110:111], 1, v[16:17]
	s_waitcnt vmcnt(15)
	v_cvt_pk_bf16_f32 v102, v32, v33
	v_cvt_pk_bf16_f32 v103, v34, v35
	s_nop 0
	global_store_dwordx2 v[16:17], v[102:103], off nt
	s_and_saveexec_b64 s[10:11], s[0:1]
	s_cbranch_execz .Lcc_skip_u8_3
	v_mov_b32_e32 v4, 0x6222000
	v_mov_b32_e32 v5, 0xe222000
	v_cndmask_b32_e32 v4, v4, v5, vcc
	v_mov_b32_e32 v5, v1
	v_lshl_add_u64 v[4:5], s[6:7], 0, v[4:5]
	v_lshl_add_u64 v[4:5], v[110:111], 2, v[4:5]
	v_add_co_u32_e32 v4, vcc, 0xffff8000, v4
	s_nop 1
	v_addc_co_u32_e32 v5, vcc, -1, v5, vcc
	s_nop 0
	global_store_dwordx4 v[4:5], v[32:35], off nt
.Lcc_skip_u8_3:
	s_or_b64 exec, exec, s[10:11]
	s_add_u32 s16, s16, s13
	v_add3_u32 v2, v9, s16, 0
	s_mov_b32 s0, 0xfffff
	v_mov_b32_e32 v4, 0x24300000
	v_cmp_lt_u32_e32 vcc, s0, v2
	v_mov_b32_e32 v5, 0x28300000
	v_mov_b32_e32 v17, v1
	v_and_b32_e32 v18, 0x3e000, v112
	v_cndmask_b32_e32 v16, v4, v5, vcc
	v_cmp_ne_u32_e64 s[0:1], 0, v18
	v_lshl_add_u64 v[16:17], s[4:5], 0, v[16:17]
	v_lshl_add_u64 v[16:17], v[112:113], 1, v[16:17]
	s_waitcnt vmcnt(15)
	v_cvt_pk_bf16_f32 v12, v36, v37
	v_cvt_pk_bf16_f32 v13, v38, v39
	s_nop 0
	global_store_dwordx2 v[16:17], v[12:13], off nt
	s_and_saveexec_b64 s[10:11], s[0:1]
	s_cbranch_execz .Lcc_skip_u8_4
	v_mov_b32_e32 v4, 0x6222000
	v_mov_b32_e32 v5, 0xe222000
	v_cndmask_b32_e32 v4, v4, v5, vcc
	v_mov_b32_e32 v5, v1
	v_lshl_add_u64 v[4:5], s[6:7], 0, v[4:5]
	v_lshl_add_u64 v[4:5], v[112:113], 2, v[4:5]
	v_add_co_u32_e32 v4, vcc, 0xffff8000, v4
	s_nop 1
	v_addc_co_u32_e32 v5, vcc, -1, v5, vcc
	s_nop 0
	global_store_dwordx4 v[4:5], v[36:39], off nt
.Lcc_skip_u8_4:
	s_or_b64 exec, exec, s[10:11]
	v_add3_u32 v2, v9, s16, 32
	s_mov_b32 s0, 0xfffff
	v_mov_b32_e32 v4, 0x24300000
	v_cmp_lt_u32_e32 vcc, s0, v2
	v_mov_b32_e32 v5, 0x28300000
	v_mov_b32_e32 v17, v1
	v_and_b32_e32 v18, 0x3e000, v114
	v_cndmask_b32_e32 v16, v4, v5, vcc
	v_cmp_ne_u32_e64 s[0:1], 0, v18
	v_lshl_add_u64 v[16:17], s[4:5], 0, v[16:17]
	v_lshl_add_u64 v[16:17], v[114:115], 1, v[16:17]
	s_waitcnt vmcnt(15)
	v_cvt_pk_bf16_f32 v14, v40, v41
	v_cvt_pk_bf16_f32 v15, v42, v43
	s_nop 0
	global_store_dwordx2 v[16:17], v[14:15], off nt
	s_and_saveexec_b64 s[10:11], s[0:1]
	s_cbranch_execz .Lcc_skip_u8_5
	v_mov_b32_e32 v4, 0x6222000
	v_mov_b32_e32 v5, 0xe222000
	v_cndmask_b32_e32 v4, v4, v5, vcc
	v_mov_b32_e32 v5, v1
	v_lshl_add_u64 v[4:5], s[6:7], 0, v[4:5]
	v_lshl_add_u64 v[4:5], v[114:115], 2, v[4:5]
	v_add_co_u32_e32 v4, vcc, 0xffff8000, v4
	s_nop 1
	v_addc_co_u32_e32 v5, vcc, -1, v5, vcc
	s_nop 0
	global_store_dwordx4 v[4:5], v[40:43], off nt
.Lcc_skip_u8_5:
	s_or_b64 exec, exec, s[10:11]
	s_add_u32 s16, s16, s13
	v_add3_u32 v2, v9, s16, 0
	s_mov_b32 s0, 0xfffff
	v_mov_b32_e32 v4, 0x24300000
	v_cmp_lt_u32_e32 vcc, s0, v2
	v_mov_b32_e32 v5, 0x28300000
	v_mov_b32_e32 v17, v1
	v_and_b32_e32 v18, 0x3e000, v116
	v_cndmask_b32_e32 v16, v4, v5, vcc
	v_cmp_ne_u32_e64 s[0:1], 0, v18
	v_lshl_add_u64 v[16:17], s[4:5], 0, v[16:17]
	v_lshl_add_u64 v[16:17], v[116:117], 1, v[16:17]
	s_waitcnt vmcnt(15)
	v_cvt_pk_bf16_f32 v100, v44, v45
	v_cvt_pk_bf16_f32 v101, v46, v47
	s_nop 0
	global_store_dwordx2 v[16:17], v[100:101], off nt
	s_and_saveexec_b64 s[10:11], s[0:1]
	s_cbranch_execz .Lcc_skip_u8_6
	v_mov_b32_e32 v4, 0x6222000
	v_mov_b32_e32 v5, 0xe222000
	v_cndmask_b32_e32 v4, v4, v5, vcc
	v_mov_b32_e32 v5, v1
	v_lshl_add_u64 v[4:5], s[6:7], 0, v[4:5]
	v_lshl_add_u64 v[4:5], v[116:117], 2, v[4:5]
	v_add_co_u32_e32 v4, vcc, 0xffff8000, v4
	s_nop 1
	v_addc_co_u32_e32 v5, vcc, -1, v5, vcc
	s_nop 0
	global_store_dwordx4 v[4:5], v[44:47], off nt
.Lcc_skip_u8_6:
	s_or_b64 exec, exec, s[10:11]
	v_add3_u32 v2, v9, s16, 32
	s_mov_b32 s0, 0xfffff
	v_mov_b32_e32 v4, 0x24300000
	v_cmp_lt_u32_e32 vcc, s0, v2
	v_mov_b32_e32 v5, 0x28300000
	v_mov_b32_e32 v17, v1
	v_and_b32_e32 v18, 0x3e000, v118
	v_cndmask_b32_e32 v16, v4, v5, vcc
	v_cmp_ne_u32_e64 s[0:1], 0, v18
	v_lshl_add_u64 v[16:17], s[4:5], 0, v[16:17]
	v_lshl_add_u64 v[16:17], v[118:119], 1, v[16:17]
	s_waitcnt vmcnt(15)
	v_cvt_pk_bf16_f32 v102, v48, v49
	v_cvt_pk_bf16_f32 v103, v50, v51
	s_nop 0
	global_store_dwordx2 v[16:17], v[102:103], off nt
	s_and_saveexec_b64 s[10:11], s[0:1]
	s_cbranch_execz .Lcc_skip_u8_7
	v_mov_b32_e32 v4, 0x6222000
	v_mov_b32_e32 v5, 0xe222000
	v_cndmask_b32_e32 v4, v4, v5, vcc
	v_mov_b32_e32 v5, v1
	v_lshl_add_u64 v[4:5], s[6:7], 0, v[4:5]
	v_lshl_add_u64 v[4:5], v[118:119], 2, v[4:5]
	v_add_co_u32_e32 v4, vcc, 0xffff8000, v4
	s_nop 1
	v_addc_co_u32_e32 v5, vcc, -1, v5, vcc
	s_nop 0
	global_store_dwordx4 v[4:5], v[48:51], off nt
.Lcc_skip_u8_7:
	s_or_b64 exec, exec, s[10:11]
	s_add_u32 s16, s16, s13
	v_add3_u32 v2, v9, s16, 0
	s_mov_b32 s0, 0xfffff
	v_mov_b32_e32 v4, 0x24300000
	v_cmp_lt_u32_e32 vcc, s0, v2
	v_mov_b32_e32 v5, 0x28300000
	v_mov_b32_e32 v17, v1
	v_and_b32_e32 v18, 0x3e000, v120
	v_cndmask_b32_e32 v16, v4, v5, vcc
	v_cmp_ne_u32_e64 s[0:1], 0, v18
	v_lshl_add_u64 v[16:17], s[4:5], 0, v[16:17]
	v_lshl_add_u64 v[16:17], v[120:121], 1, v[16:17]
	s_waitcnt vmcnt(15)
	v_cvt_pk_bf16_f32 v12, v52, v53
	v_cvt_pk_bf16_f32 v13, v54, v55
	s_nop 0
	global_store_dwordx2 v[16:17], v[12:13], off nt
	s_and_saveexec_b64 s[10:11], s[0:1]
	s_cbranch_execz .Lcc_skip_u8_8
	v_mov_b32_e32 v4, 0x6222000
	v_mov_b32_e32 v5, 0xe222000
	v_cndmask_b32_e32 v4, v4, v5, vcc
	v_mov_b32_e32 v5, v1
	v_lshl_add_u64 v[4:5], s[6:7], 0, v[4:5]
	v_lshl_add_u64 v[4:5], v[120:121], 2, v[4:5]
	v_add_co_u32_e32 v4, vcc, 0xffff8000, v4
	s_nop 1
	v_addc_co_u32_e32 v5, vcc, -1, v5, vcc
	s_nop 0
	global_store_dwordx4 v[4:5], v[52:55], off nt
; __device__ __forceinline__ void cache_convert(const Params& P, int l, int pct0, int pct1, int part, int nparts) {
;     ...
;     for (unsigned gi = g0 + (unsigned)part * 512u + tid; gi < g1; gi += (unsigned)nparts * 512u) {
;         const bool isv = gi >= NGL; const unsigned e = (isv ? gi - NGL : gi) * 8u; const int key = (int)((e >> 9) & 511u);
;         const float* src = (isv ? cv : ck) + e;
;         const f32x4 k0 = *(const f32x4*)src, k1 = *(const f32x4*)(src + 4);
;         *(bf16x8*)((isv ? vb : kb) + e) = pack8v(k0, k1);
;         if (key >= 16) { float* d = (isv ? ov : ok) + e - 16 * 512; *(f32x4*)d = k0; *(f32x4*)(d + 4) = k1; }
.Lcc_skip_u8_8:
	s_or_b64 exec, exec, s[10:11]
	v_add3_u32 v2, v9, s16, 32
	s_mov_b32 s0, 0xfffff
	v_mov_b32_e32 v4, 0x24300000
	v_cmp_lt_u32_e32 vcc, s0, v2
	v_mov_b32_e32 v5, 0x28300000
	v_mov_b32_e32 v17, v1
	v_and_b32_e32 v18, 0x3e000, v122
	v_cndmask_b32_e32 v16, v4, v5, vcc
	v_cmp_ne_u32_e64 s[0:1], 0, v18
	v_lshl_add_u64 v[16:17], s[4:5], 0, v[16:17]
	v_lshl_add_u64 v[16:17], v[122:123], 1, v[16:17]
	s_waitcnt vmcnt(15)
	v_cvt_pk_bf16_f32 v14, v56, v57
	v_cvt_pk_bf16_f32 v15, v58, v59
	s_nop 0
	global_store_dwordx2 v[16:17], v[14:15], off nt
	s_and_saveexec_b64 s[10:11], s[0:1]
	s_cbranch_execz .Lcc_skip_u8_9
	v_mov_b32_e32 v4, 0x6222000
	v_mov_b32_e32 v5, 0xe222000
	v_cndmask_b32_e32 v4, v4, v5, vcc
	v_mov_b32_e32 v5, v1
	v_lshl_add_u64 v[4:5], s[6:7], 0, v[4:5]
	v_lshl_add_u64 v[4:5], v[122:123], 2, v[4:5]
	v_add_co_u32_e32 v4, vcc, 0xffff8000, v4
	s_nop 1
	v_addc_co_u32_e32 v5, vcc, -1, v5, vcc
	s_nop 0
	global_store_dwordx4 v[4:5], v[56:59], off nt
.Lcc_skip_u8_9:
	s_or_b64 exec, exec, s[10:11]
	s_add_u32 s16, s16, s13
	v_add3_u32 v2, v9, s16, 0
	s_mov_b32 s0, 0xfffff
	v_mov_b32_e32 v4, 0x24300000
	v_cmp_lt_u32_e32 vcc, s0, v2
	v_mov_b32_e32 v5, 0x28300000
	v_mov_b32_e32 v17, v1
	v_and_b32_e32 v18, 0x3e000, v124
	v_cndmask_b32_e32 v16, v4, v5, vcc
	v_cmp_ne_u32_e64 s[0:1], 0, v18
	v_lshl_add_u64 v[16:17], s[4:5], 0, v[16:17]
	v_lshl_add_u64 v[16:17], v[124:125], 1, v[16:17]
	s_waitcnt vmcnt(15)
	v_cvt_pk_bf16_f32 v100, v60, v61
	v_cvt_pk_bf16_f32 v101, v62, v63
	s_nop 0
	global_store_dwordx2 v[16:17], v[100:101], off nt
	s_and_saveexec_b64 s[10:11], s[0:1]
	s_cbranch_execz .Lcc_skip_u8_10
	v_mov_b32_e32 v4, 0x6222000
	v_mov_b32_e32 v5, 0xe222000
	v_cndmask_b32_e32 v4, v4, v5, vcc
	v_mov_b32_e32 v5, v1
	v_lshl_add_u64 v[4:5], s[6:7], 0, v[4:5]
	v_lshl_add_u64 v[4:5], v[124:125], 2, v[4:5]
	v_add_co_u32_e32 v4, vcc, 0xffff8000, v4
	s_nop 1
	v_addc_co_u32_e32 v5, vcc, -1, v5, vcc
	s_nop 0
	global_store_dwordx4 v[4:5], v[60:63], off nt
.Lcc_skip_u8_10:
	s_or_b64 exec, exec, s[10:11]
	v_add3_u32 v2, v9, s16, 32
	s_mov_b32 s0, 0xfffff
	v_mov_b32_e32 v4, 0x24300000
	v_cmp_lt_u32_e32 vcc, s0, v2
	v_mov_b32_e32 v5, 0x28300000
	v_mov_b32_e32 v17, v1
	v_and_b32_e32 v18, 0x3e000, v126
	v_cndmask_b32_e32 v16, v4, v5, vcc
	v_cmp_ne_u32_e64 s[0:1], 0, v18
	v_lshl_add_u64 v[16:17], s[4:5], 0, v[16:17]
	v_lshl_add_u64 v[16:17], v[126:127], 1, v[16:17]
	s_waitcnt vmcnt(15)
	v_cvt_pk_bf16_f32 v102, v64, v65
	v_cvt_pk_bf16_f32 v103, v66, v67
	s_nop 0
	global_store_dwordx2 v[16:17], v[102:103], off nt
	s_and_saveexec_b64 s[10:11], s[0:1]
	s_cbranch_execz .Lcc_skip_u8_11
	v_mov_b32_e32 v4, 0x6222000
	v_mov_b32_e32 v5, 0xe222000
	v_cndmask_b32_e32 v4, v4, v5, vcc
	v_mov_b32_e32 v5, v1
	v_lshl_add_u64 v[4:5], s[6:7], 0, v[4:5]
	v_lshl_add_u64 v[4:5], v[126:127], 2, v[4:5]
	v_add_co_u32_e32 v4, vcc, 0xffff8000, v4
	s_nop 1
	v_addc_co_u32_e32 v5, vcc, -1, v5, vcc
	s_nop 0
	global_store_dwordx4 v[4:5], v[64:67], off nt
.Lcc_skip_u8_11:
	s_or_b64 exec, exec, s[10:11]
	s_add_u32 s16, s16, s13
	v_add3_u32 v2, v9, s16, 0
	s_mov_b32 s0, 0xfffff
	v_mov_b32_e32 v4, 0x24300000
	v_cmp_lt_u32_e32 vcc, s0, v2
	v_mov_b32_e32 v5, 0x28300000
	v_mov_b32_e32 v17, v1
	v_and_b32_e32 v18, 0x3e000, v128
	v_cndmask_b32_e32 v16, v4, v5, vcc
	v_cmp_ne_u32_e64 s[0:1], 0, v18
	v_lshl_add_u64 v[16:17], s[4:5], 0, v[16:17]
	v_lshl_add_u64 v[16:17], v[128:129], 1, v[16:17]
	s_waitcnt vmcnt(15)
	v_cvt_pk_bf16_f32 v12, v68, v69
	v_cvt_pk_bf16_f32 v13, v70, v71
	s_nop 0
	global_store_dwordx2 v[16:17], v[12:13], off nt
	s_and_saveexec_b64 s[10:11], s[0:1]
	s_cbranch_execz .Lcc_skip_u8_12
	v_mov_b32_e32 v4, 0x6222000
	v_mov_b32_e32 v5, 0xe222000
	v_cndmask_b32_e32 v4, v4, v5, vcc
	v_mov_b32_e32 v5, v1
	v_lshl_add_u64 v[4:5], s[6:7], 0, v[4:5]
	v_lshl_add_u64 v[4:5], v[128:129], 2, v[4:5]
	v_add_co_u32_e32 v4, vcc, 0xffff8000, v4
	s_nop 1
	v_addc_co_u32_e32 v5, vcc, -1, v5, vcc
	s_nop 0
	global_store_dwordx4 v[4:5], v[68:71], off nt
.Lcc_skip_u8_12:
	s_or_b64 exec, exec, s[10:11]
	v_add3_u32 v2, v9, s16, 32
	s_mov_b32 s0, 0xfffff
	v_mov_b32_e32 v4, 0x24300000
	v_cmp_lt_u32_e32 vcc, s0, v2
	v_mov_b32_e32 v5, 0x28300000
	v_mov_b32_e32 v17, v1
	v_and_b32_e32 v18, 0x3e000, v130
	v_cndmask_b32_e32 v16, v4, v5, vcc
	v_cmp_ne_u32_e64 s[0:1], 0, v18
	v_lshl_add_u64 v[16:17], s[4:5], 0, v[16:17]
	v_lshl_add_u64 v[16:17], v[130:131], 1, v[16:17]
	s_waitcnt vmcnt(15)
	v_cvt_pk_bf16_f32 v14, v72, v73
	v_cvt_pk_bf16_f32 v15, v74, v75
	s_nop 0
	global_store_dwordx2 v[16:17], v[14:15], off nt
	s_and_saveexec_b64 s[10:11], s[0:1]
	s_cbranch_execz .Lcc_skip_u8_13
	v_mov_b32_e32 v4, 0x6222000
	v_mov_b32_e32 v5, 0xe222000
	v_cndmask_b32_e32 v4, v4, v5, vcc
	v_mov_b32_e32 v5, v1
	v_lshl_add_u64 v[4:5], s[6:7], 0, v[4:5]
	v_lshl_add_u64 v[4:5], v[130:131], 2, v[4:5]
	v_add_co_u32_e32 v4, vcc, 0xffff8000, v4
	s_nop 1
	v_addc_co_u32_e32 v5, vcc, -1, v5, vcc
	s_nop 0
	global_store_dwordx4 v[4:5], v[72:75], off nt
.Lcc_skip_u8_13:
	s_or_b64 exec, exec, s[10:11]
	s_add_u32 s16, s16, s13
	v_add3_u32 v2, v9, s16, 0
	s_mov_b32 s0, 0xfffff
	v_mov_b32_e32 v4, 0x24300000
	v_cmp_lt_u32_e32 vcc, s0, v2
	v_mov_b32_e32 v5, 0x28300000
	v_mov_b32_e32 v17, v1
	v_and_b32_e32 v18, 0x3e000, v132
	v_cndmask_b32_e32 v16, v4, v5, vcc
	v_cmp_ne_u32_e64 s[0:1], 0, v18
	v_lshl_add_u64 v[16:17], s[4:5], 0, v[16:17]
	v_lshl_add_u64 v[16:17], v[132:133], 1, v[16:17]
	s_waitcnt vmcnt(15)
	v_cvt_pk_bf16_f32 v100, v76, v77
	v_cvt_pk_bf16_f32 v101, v78, v79
	s_nop 0
	global_store_dwordx2 v[16:17], v[100:101], off nt
	s_and_saveexec_b64 s[10:11], s[0:1]
	s_cbranch_execz .Lcc_skip_u8_14
	v_mov_b32_e32 v4, 0x6222000
	v_mov_b32_e32 v5, 0xe222000
	v_cndmask_b32_e32 v4, v4, v5, vcc
	v_mov_b32_e32 v5, v1
	v_lshl_add_u64 v[4:5], s[6:7], 0, v[4:5]
	v_lshl_add_u64 v[4:5], v[132:133], 2, v[4:5]
	v_add_co_u32_e32 v4, vcc, 0xffff8000, v4
	s_nop 1
	v_addc_co_u32_e32 v5, vcc, -1, v5, vcc
	s_nop 0
	global_store_dwordx4 v[4:5], v[76:79], off nt
.Lcc_skip_u8_14:
	s_or_b64 exec, exec, s[10:11]
	v_add3_u32 v2, v9, s16, 32
	s_mov_b32 s0, 0xfffff
	v_mov_b32_e32 v4, 0x24300000
	v_cmp_lt_u32_e32 vcc, s0, v2
	v_mov_b32_e32 v5, 0x28300000
	v_mov_b32_e32 v17, v1
	v_and_b32_e32 v18, 0x3e000, v134
	v_cndmask_b32_e32 v16, v4, v5, vcc
	v_cmp_ne_u32_e64 s[0:1], 0, v18
	v_lshl_add_u64 v[16:17], s[4:5], 0, v[16:17]
	v_lshl_add_u64 v[16:17], v[134:135], 1, v[16:17]
	s_waitcnt vmcnt(15)
	v_cvt_pk_bf16_f32 v102, v80, v81
	v_cvt_pk_bf16_f32 v103, v82, v83
	s_nop 0
	global_store_dwordx2 v[16:17], v[102:103], off nt
	s_and_saveexec_b64 s[10:11], s[0:1]
	s_cbranch_execz .Lcc_skip_u8_15
	v_mov_b32_e32 v4, 0x6222000
	v_mov_b32_e32 v5, 0xe222000
	v_cndmask_b32_e32 v4, v4, v5, vcc
	v_mov_b32_e32 v5, v1
	v_lshl_add_u64 v[4:5], s[6:7], 0, v[4:5]
	v_lshl_add_u64 v[4:5], v[134:135], 2, v[4:5]
	v_add_co_u32_e32 v4, vcc, 0xffff8000, v4
	s_nop 1
	v_addc_co_u32_e32 v5, vcc, -1, v5, vcc
	s_nop 0
	global_store_dwordx4 v[4:5], v[80:83], off nt

; __device__ __forceinline__ void cache_convert(const Params& P, int l, int pct0, int pct1, int part, int nparts) {
;     int tid = threadIdx.x; asm volatile("" : "+v"(tid));
;     constexpr unsigned NGL = 32u * 512u * 512u / 8u;
;     const unsigned g0 = (unsigned)((unsigned long long)(2u * NGL) * pct0 / 100u), g1 = (unsigned)((unsigned long long)(2u * NGL) * pct1 / 100u);
;     const float* ck = P.in[3] + (size_t)l * 32 * 512 * 512; const float* cv = P.in[4] + (size_t)l * 32 * 512 * 512;
;     bf16_t* kb = (bf16_t*)(P.ws + WS_KB16) + (size_t)l * 32 * 512 * 512; bf16_t* vb = (bf16_t*)(P.ws + WS_VB16) + (size_t)l * 32 * 512 * 512;
;     float* ok = P.out + OFF_KS + (size_t)l * 32 * 512 * 512; float* ov = P.out + OFF_VS + (size_t)l * 32 * 512 * 512;
; #pragma unroll 8
;     for (unsigned gi = g0 + (unsigned)part * 512u + tid; gi < g1; gi += (unsigned)nparts * 512u) {
;         const bool isv = gi >= NGL; const unsigned e = (isv ? gi - NGL : gi) * 8u; const int key = (int)((e >> 9) & 511u);
;         const float* src = (isv ? cv : ck) + e;
;         const f32x4 k0 = *(const f32x4*)src, k1 = *(const f32x4*)(src + 4);
;         *(bf16x8*)((isv ? vb : kb) + e) = pack8v(k0, k1);
;         if (key >= 16) { float* d = (isv ? ov : ok) + e - 16 * 512; *(f32x4*)d = k0; *(f32x4*)(d + 4) = k1; }
;     }
.Lcc_try4:
	v_readlane_b32 s16, v10, 63
	s_mul_i32 s17, s13, 3
	s_add_u32 s16, s16, s17
	s_cmp_lt_u32 s16, s12
	s_cbranch_scc0 .Lcc_try2
	v_readlane_b32 s22, v253, 61
	v_readlane_b32 s23, v253, 62
	v_readlane_b32 s24, v253, 63
	v_readlane_b32 s25, v254, 0
	s_mov_b64 s[18:19], s[22:23]
	s_mov_b64 s[20:21], s[24:25]
	s_mov_b32 s0, 0xfffff
	s_mov_b32 s16, 0
	v_and_b32_e32 v2, 63, v208
	v_add_u32_e32 v3, 1, v2
	v_lshrrev_b32_e32 v3, 1, v3
	v_and_b32_e32 v2, 1, v2
	v_sub_u32_e32 v9, v10, v3
	v_lshlrev_b32_e32 v19, 2, v2
	v_mov_b32_e32 v105, 0
	v_mov_b32_e32 v107, 0
	v_mov_b32_e32 v109, 0
	v_mov_b32_e32 v111, 0
	v_mov_b32_e32 v113, 0
	v_mov_b32_e32 v115, 0
	v_mov_b32_e32 v117, 0
	v_mov_b32_e32 v119, 0
	v_add3_u32 v2, v9, s16, 0
	s_nop 0
	v_cmp_lt_u32_e32 vcc, s0, v2
	v_lshl_add_u32 v3, v2, 3, v19
	v_mov_b32_e32 v5, s19
	v_add_u32_e32 v4, 0xff800000, v3
	v_mov_b32_e32 v6, s21
	v_cndmask_b32_e32 v104, v3, v4, vcc
	v_cndmask_b32_e32 v7, v5, v6, vcc
	v_mov_b32_e32 v5, s18
	v_mov_b32_e32 v8, s20
	v_cndmask_b32_e32 v6, v5, v8, vcc
	v_lshl_add_u64 v[6:7], v[6:7], 0, s[62:63]
	v_lshl_add_u64 v[6:7], v[104:105], 2, v[6:7]
	global_load_dwordx4 v[20:23], v[6:7], off nt
	v_add3_u32 v2, v9, s16, 32
	s_nop 0
	v_cmp_lt_u32_e32 vcc, s0, v2
	v_lshl_add_u32 v3, v2, 3, v19
	v_mov_b32_e32 v5, s19
	v_add_u32_e32 v4, 0xff800000, v3
	v_mov_b32_e32 v6, s21
	v_cndmask_b32_e32 v106, v3, v4, vcc
	v_cndmask_b32_e32 v7, v5, v6, vcc
	v_mov_b32_e32 v5, s18
	v_mov_b32_e32 v8, s20
	v_cndmask_b32_e32 v6, v5, v8, vcc
	v_lshl_add_u64 v[6:7], v[6:7], 0, s[62:63]
	v_lshl_add_u64 v[6:7], v[106:107], 2, v[6:7]
	global_load_dwordx4 v[24:27], v[6:7], off nt
	s_add_u32 s16, s16, s13
	v_add3_u32 v2, v9, s16, 0
	s_nop 0
	v_cmp_lt_u32_e32 vcc, s0, v2
	v_lshl_add_u32 v3, v2, 3, v19
	v_mov_b32_e32 v5, s19
	v_add_u32_e32 v4, 0xff800000, v3
	v_mov_b32_e32 v6, s21
	v_cndmask_b32_e32 v108, v3, v4, vcc
	v_cndmask_b32_e32 v7, v5, v6, vcc
	v_mov_b32_e32 v5, s18
	v_mov_b32_e32 v8, s20
	v_cndmask_b32_e32 v6, v5, v8, vcc
	v_lshl_add_u64 v[6:7], v[6:7], 0, s[62:63]
	v_lshl_add_u64 v[6:7], v[108:109], 2, v[6:7]
	global_load_dwordx4 v[28:31], v[6:7], off nt
	v_add3_u32 v2, v9, s16, 32
	s_nop 0
	v_cmp_lt_u32_e32 vcc, s0, v2
	v_lshl_add_u32 v3, v2, 3, v19
	v_mov_b32_e32 v5, s19
	v_add_u32_e32 v4, 0xff800000, v3
	v_mov_b32_e32 v6, s21
	v_cndmask_b32_e32 v110, v3, v4, vcc
	v_cndmask_b32_e32 v7, v5, v6, vcc
	v_mov_b32_e32 v5, s18
	v_mov_b32_e32 v8, s20
	v_cndmask_b32_e32 v6, v5, v8, vcc
	v_lshl_add_u64 v[6:7], v[6:7], 0, s[62:63]
	v_lshl_add_u64 v[6:7], v[110:111], 2, v[6:7]
	global_load_dwordx4 v[32:35], v[6:7], off nt
	s_add_u32 s16, s16, s13
	v_add3_u32 v2, v9, s16, 0
	s_nop 0
	v_cmp_lt_u32_e32 vcc, s0, v2
	v_lshl_add_u32 v3, v2, 3, v19
	v_mov_b32_e32 v5, s19
	v_add_u32_e32 v4, 0xff800000, v3
	v_mov_b32_e32 v6, s21
	v_cndmask_b32_e32 v112, v3, v4, vcc
	v_cndmask_b32_e32 v7, v5, v6, vcc
	v_mov_b32_e32 v5, s18
	v_mov_b32_e32 v8, s20
	v_cndmask_b32_e32 v6, v5, v8, vcc
	v_lshl_add_u64 v[6:7], v[6:7], 0, s[62:63]
	v_lshl_add_u64 v[6:7], v[112:113], 2, v[6:7]
	global_load_dwordx4 v[36:39], v[6:7], off nt
	v_add3_u32 v2, v9, s16, 32
	s_nop 0
	v_cmp_lt_u32_e32 vcc, s0, v2
	v_lshl_add_u32 v3, v2, 3, v19
	v_mov_b32_e32 v5, s19
	v_add_u32_e32 v4, 0xff800000, v3
	v_mov_b32_e32 v6, s21
	v_cndmask_b32_e32 v114, v3, v4, vcc
	v_cndmask_b32_e32 v7, v5, v6, vcc
	v_mov_b32_e32 v5, s18
	v_mov_b32_e32 v8, s20
	v_cndmask_b32_e32 v6, v5, v8, vcc
	v_lshl_add_u64 v[6:7], v[6:7], 0, s[62:63]
	v_lshl_add_u64 v[6:7], v[114:115], 2, v[6:7]
	global_load_dwordx4 v[40:43], v[6:7], off nt
	s_add_u32 s16, s16, s13
	v_add3_u32 v2, v9, s16, 0
	s_nop 0
	v_cmp_lt_u32_e32 vcc, s0, v2
	v_lshl_add_u32 v3, v2, 3, v19
	v_mov_b32_e32 v5, s19
	v_add_u32_e32 v4, 0xff800000, v3
	v_mov_b32_e32 v6, s21
	v_cndmask_b32_e32 v116, v3, v4, vcc
	v_cndmask_b32_e32 v7, v5, v6, vcc
	v_mov_b32_e32 v5, s18
	v_mov_b32_e32 v8, s20
	v_cndmask_b32_e32 v6, v5, v8, vcc
	v_lshl_add_u64 v[6:7], v[6:7], 0, s[62:63]
	v_lshl_add_u64 v[6:7], v[116:117], 2, v[6:7]
	global_load_dwordx4 v[44:47], v[6:7], off nt
	v_add3_u32 v2, v9, s16, 32
	s_nop 0
	v_cmp_lt_u32_e32 vcc, s0, v2
	v_lshl_add_u32 v3, v2, 3, v19
	v_mov_b32_e32 v5, s19
	v_add_u32_e32 v4, 0xff800000, v3
	v_mov_b32_e32 v6, s21
	v_cndmask_b32_e32 v118, v3, v4, vcc
	v_cndmask_b32_e32 v7, v5, v6, vcc
	v_mov_b32_e32 v5, s18
	v_mov_b32_e32 v8, s20
	v_cndmask_b32_e32 v6, v5, v8, vcc
	v_lshl_add_u64 v[6:7], v[6:7], 0, s[62:63]
	v_lshl_add_u64 v[6:7], v[118:119], 2, v[6:7]
	global_load_dwordx4 v[48:51], v[6:7], off nt
	s_mov_b32 s16, 0
	v_add3_u32 v2, v9, s16, 0
	s_mov_b32 s0, 0xfffff
	v_mov_b32_e32 v4, 0x24300000
	v_cmp_lt_u32_e32 vcc, s0, v2
	v_mov_b32_e32 v5, 0x28300000
	v_mov_b32_e32 v17, v1
	v_and_b32_e32 v18, 0x3e000, v104
	v_cndmask_b32_e32 v16, v4, v5, vcc
	v_cmp_ne_u32_e64 s[0:1], 0, v18
	v_lshl_add_u64 v[16:17], s[4:5], 0, v[16:17]
	v_lshl_add_u64 v[16:17], v[104:105], 1, v[16:17]
	s_waitcnt vmcnt(7)
	v_cvt_pk_bf16_f32 v12, v20, v21
	v_cvt_pk_bf16_f32 v13, v22, v23
	s_nop 0
	global_store_dwordx2 v[16:17], v[12:13], off nt
	s_and_saveexec_b64 s[10:11], s[0:1]
	s_cbranch_execz .Lcc_skip_u4_0
	v_mov_b32_e32 v4, 0x6222000
	v_mov_b32_e32 v5, 0xe222000
	v_cndmask_b32_e32 v4, v4, v5, vcc
	v_mov_b32_e32 v5, v1
	v_lshl_add_u64 v[4:5], s[6:7], 0, v[4:5]
	v_lshl_add_u64 v[4:5], v[104:105], 2, v[4:5]
	v_add_co_u32_e32 v4, vcc, 0xffff8000, v4
	s_nop 1
	v_addc_co_u32_e32 v5, vcc, -1, v5, vcc
	s_nop 0
	global_store_dwordx4 v[4:5], v[20:23], off nt
; __device__ __forceinline__ void cache_convert(const Params& P, int l, int pct0, int pct1, int part, int nparts) {
;     ...
;     for (unsigned gi = g0 + (unsigned)part * 512u + tid; gi < g1; gi += (unsigned)nparts * 512u) {
;         const bool isv = gi >= NGL; const unsigned e = (isv ? gi - NGL : gi) * 8u; const int key = (int)((e >> 9) & 511u);
;         const float* src = (isv ? cv : ck) + e;
;         const f32x4 k0 = *(const f32x4*)src, k1 = *(const f32x4*)(src + 4);
;         *(bf16x8*)((isv ? vb : kb) + e) = pack8v(k0, k1);
;         if (key >= 16) { float* d = (isv ? ov : ok) + e - 16 * 512; *(f32x4*)d = k0; *(f32x4*)(d + 4) = k1; }
.Lcc_skip_u4_0:
	s_or_b64 exec, exec, s[10:11]
	v_add3_u32 v2, v9, s16, 32
	s_mov_b32 s0, 0xfffff
	v_mov_b32_e32 v4, 0x24300000
	v_cmp_lt_u32_e32 vcc, s0, v2
	v_mov_b32_e32 v5, 0x28300000
	v_mov_b32_e32 v17, v1
	v_and_b32_e32 v18, 0x3e000, v106
	v_cndmask_b32_e32 v16, v4, v5, vcc
	v_cmp_ne_u32_e64 s[0:1], 0, v18
	v_lshl_add_u64 v[16:17], s[4:5], 0, v[16:17]
	v_lshl_add_u64 v[16:17], v[106:107], 1, v[16:17]
	s_waitcnt vmcnt(7)
	v_cvt_pk_bf16_f32 v14, v24, v25
	v_cvt_pk_bf16_f32 v15, v26, v27
	s_nop 0
	global_store_dwordx2 v[16:17], v[14:15], off nt
	s_and_saveexec_b64 s[10:11], s[0:1]
	s_cbranch_execz .Lcc_skip_u4_1
	v_mov_b32_e32 v4, 0x6222000
	v_mov_b32_e32 v5, 0xe222000
	v_cndmask_b32_e32 v4, v4, v5, vcc
	v_mov_b32_e32 v5, v1
	v_lshl_add_u64 v[4:5], s[6:7], 0, v[4:5]
	v_lshl_add_u64 v[4:5], v[106:107], 2, v[4:5]
	v_add_co_u32_e32 v4, vcc, 0xffff8000, v4
	s_nop 1
	v_addc_co_u32_e32 v5, vcc, -1, v5, vcc
	s_nop 0
	global_store_dwordx4 v[4:5], v[24:27], off nt
.Lcc_skip_u4_1:
	s_or_b64 exec, exec, s[10:11]
	s_add_u32 s16, s16, s13
	v_add3_u32 v2, v9, s16, 0
	s_mov_b32 s0, 0xfffff
	v_mov_b32_e32 v4, 0x24300000
	v_cmp_lt_u32_e32 vcc, s0, v2
	v_mov_b32_e32 v5, 0x28300000
	v_mov_b32_e32 v17, v1
	v_and_b32_e32 v18, 0x3e000, v108
	v_cndmask_b32_e32 v16, v4, v5, vcc
	v_cmp_ne_u32_e64 s[0:1], 0, v18
	v_lshl_add_u64 v[16:17], s[4:5], 0, v[16:17]
	v_lshl_add_u64 v[16:17], v[108:109], 1, v[16:17]
	s_waitcnt vmcnt(7)
	v_cvt_pk_bf16_f32 v100, v28, v29
	v_cvt_pk_bf16_f32 v101, v30, v31
	s_nop 0
	global_store_dwordx2 v[16:17], v[100:101], off nt
	s_and_saveexec_b64 s[10:11], s[0:1]
	s_cbranch_execz .Lcc_skip_u4_2
	v_mov_b32_e32 v4, 0x6222000
	v_mov_b32_e32 v5, 0xe222000
	v_cndmask_b32_e32 v4, v4, v5, vcc
	v_mov_b32_e32 v5, v1
	v_lshl_add_u64 v[4:5], s[6:7], 0, v[4:5]
	v_lshl_add_u64 v[4:5], v[108:109], 2, v[4:5]
	v_add_co_u32_e32 v4, vcc, 0xffff8000, v4
	s_nop 1
	v_addc_co_u32_e32 v5, vcc, -1, v5, vcc
	s_nop 0
	global_store_dwordx4 v[4:5], v[28:31], off nt
.Lcc_skip_u4_2:
	s_or_b64 exec, exec, s[10:11]
	v_add3_u32 v2, v9, s16, 32
	s_mov_b32 s0, 0xfffff
	v_mov_b32_e32 v4, 0x24300000
	v_cmp_lt_u32_e32 vcc, s0, v2
	v_mov_b32_e32 v5, 0x28300000
	v_mov_b32_e32 v17, v1
	v_and_b32_e32 v18, 0x3e000, v110
	v_cndmask_b32_e32 v16, v4, v5, vcc
	v_cmp_ne_u32_e64 s[0:1], 0, v18
	v_lshl_add_u64 v[16:17], s[4:5], 0, v[16:17]
	v_lshl_add_u64 v[16:17], v[110:111], 1, v[16:17]
	s_waitcnt vmcnt(7)
	v_cvt_pk_bf16_f32 v102, v32, v33
	v_cvt_pk_bf16_f32 v103, v34, v35
	s_nop 0
	global_store_dwordx2 v[16:17], v[102:103], off nt
	s_and_saveexec_b64 s[10:11], s[0:1]
	s_cbranch_execz .Lcc_skip_u4_3
	v_mov_b32_e32 v4, 0x6222000
	v_mov_b32_e32 v5, 0xe222000
	v_cndmask_b32_e32 v4, v4, v5, vcc
	v_mov_b32_e32 v5, v1
	v_lshl_add_u64 v[4:5], s[6:7], 0, v[4:5]
	v_lshl_add_u64 v[4:5], v[110:111], 2, v[4:5]
	v_add_co_u32_e32 v4, vcc, 0xffff8000, v4
	s_nop 1
	v_addc_co_u32_e32 v5, vcc, -1, v5, vcc
	s_nop 0
	global_store_dwordx4 v[4:5], v[32:35], off nt
.Lcc_skip_u4_3:
	s_or_b64 exec, exec, s[10:11]
	s_add_u32 s16, s16, s13
	v_add3_u32 v2, v9, s16, 0
	s_mov_b32 s0, 0xfffff
	v_mov_b32_e32 v4, 0x24300000
	v_cmp_lt_u32_e32 vcc, s0, v2
	v_mov_b32_e32 v5, 0x28300000
	v_mov_b32_e32 v17, v1
	v_and_b32_e32 v18, 0x3e000, v112
	v_cndmask_b32_e32 v16, v4, v5, vcc
	v_cmp_ne_u32_e64 s[0:1], 0, v18
	v_lshl_add_u64 v[16:17], s[4:5], 0, v[16:17]
	v_lshl_add_u64 v[16:17], v[112:113], 1, v[16:17]
	s_waitcnt vmcnt(7)
	v_cvt_pk_bf16_f32 v12, v36, v37
	v_cvt_pk_bf16_f32 v13, v38, v39
	s_nop 0
	global_store_dwordx2 v[16:17], v[12:13], off nt
	s_and_saveexec_b64 s[10:11], s[0:1]
	s_cbranch_execz .Lcc_skip_u4_4
	v_mov_b32_e32 v4, 0x6222000
	v_mov_b32_e32 v5, 0xe222000
	v_cndmask_b32_e32 v4, v4, v5, vcc
	v_mov_b32_e32 v5, v1
	v_lshl_add_u64 v[4:5], s[6:7], 0, v[4:5]
	v_lshl_add_u64 v[4:5], v[112:113], 2, v[4:5]
	v_add_co_u32_e32 v4, vcc, 0xffff8000, v4
	s_nop 1
	v_addc_co_u32_e32 v5, vcc, -1, v5, vcc
	s_nop 0
	global_store_dwordx4 v[4:5], v[36:39], off nt
.Lcc_skip_u4_4:
	s_or_b64 exec, exec, s[10:11]
	v_add3_u32 v2, v9, s16, 32
	s_mov_b32 s0, 0xfffff
	v_mov_b32_e32 v4, 0x24300000
	v_cmp_lt_u32_e32 vcc, s0, v2
	v_mov_b32_e32 v5, 0x28300000
	v_mov_b32_e32 v17, v1
	v_and_b32_e32 v18, 0x3e000, v114
	v_cndmask_b32_e32 v16, v4, v5, vcc
	v_cmp_ne_u32_e64 s[0:1], 0, v18
	v_lshl_add_u64 v[16:17], s[4:5], 0, v[16:17]
	v_lshl_add_u64 v[16:17], v[114:115], 1, v[16:17]
	s_waitcnt vmcnt(7)
	v_cvt_pk_bf16_f32 v14, v40, v41
	v_cvt_pk_bf16_f32 v15, v42, v43
	s_nop 0
	global_store_dwordx2 v[16:17], v[14:15], off nt
	s_and_saveexec_b64 s[10:11], s[0:1]
	s_cbranch_execz .Lcc_skip_u4_5
	v_mov_b32_e32 v4, 0x6222000
	v_mov_b32_e32 v5, 0xe222000
	v_cndmask_b32_e32 v4, v4, v5, vcc
	v_mov_b32_e32 v5, v1
	v_lshl_add_u64 v[4:5], s[6:7], 0, v[4:5]
	v_lshl_add_u64 v[4:5], v[114:115], 2, v[4:5]
	v_add_co_u32_e32 v4, vcc, 0xffff8000, v4
	s_nop 1
	v_addc_co_u32_e32 v5, vcc, -1, v5, vcc
	s_nop 0
	global_store_dwordx4 v[4:5], v[40:43], off nt
.Lcc_skip_u4_5:
	s_or_b64 exec, exec, s[10:11]
	s_add_u32 s16, s16, s13
	v_add3_u32 v2, v9, s16, 0
	s_mov_b32 s0, 0xfffff
	v_mov_b32_e32 v4, 0x24300000
	v_cmp_lt_u32_e32 vcc, s0, v2
	v_mov_b32_e32 v5, 0x28300000
	v_mov_b32_e32 v17, v1
	v_and_b32_e32 v18, 0x3e000, v116
	v_cndmask_b32_e32 v16, v4, v5, vcc
	v_cmp_ne_u32_e64 s[0:1], 0, v18
	v_lshl_add_u64 v[16:17], s[4:5], 0, v[16:17]
	v_lshl_add_u64 v[16:17], v[116:117], 1, v[16:17]
	s_waitcnt vmcnt(7)
	v_cvt_pk_bf16_f32 v100, v44, v45
	v_cvt_pk_bf16_f32 v101, v46, v47
	s_nop 0
	global_store_dwordx2 v[16:17], v[100:101], off nt
	s_and_saveexec_b64 s[10:11], s[0:1]
	s_cbranch_execz .Lcc_skip_u4_6
	v_mov_b32_e32 v4, 0x6222000
	v_mov_b32_e32 v5, 0xe222000
	v_cndmask_b32_e32 v4, v4, v5, vcc
	v_mov_b32_e32 v5, v1
	v_lshl_add_u64 v[4:5], s[6:7], 0, v[4:5]
	v_lshl_add_u64 v[4:5], v[116:117], 2, v[4:5]
	v_add_co_u32_e32 v4, vcc, 0xffff8000, v4
	s_nop 1
	v_addc_co_u32_e32 v5, vcc, -1, v5, vcc
	s_nop 0
	global_store_dwordx4 v[4:5], v[44:47], off nt
.Lcc_skip_u4_6:
	s_or_b64 exec, exec, s[10:11]
	v_add3_u32 v2, v9, s16, 32
	s_mov_b32 s0, 0xfffff
	v_mov_b32_e32 v4, 0x24300000
	v_cmp_lt_u32_e32 vcc, s0, v2
	v_mov_b32_e32 v5, 0x28300000
	v_mov_b32_e32 v17, v1
	v_and_b32_e32 v18, 0x3e000, v118
	v_cndmask_b32_e32 v16, v4, v5, vcc
	v_cmp_ne_u32_e64 s[0:1], 0, v18
	v_lshl_add_u64 v[16:17], s[4:5], 0, v[16:17]
	v_lshl_add_u64 v[16:17], v[118:119], 1, v[16:17]
	s_waitcnt vmcnt(7)
	v_cvt_pk_bf16_f32 v102, v48, v49
	v_cvt_pk_bf16_f32 v103, v50, v51
	s_nop 0
	global_store_dwordx2 v[16:17], v[102:103], off nt
	s_and_saveexec_b64 s[10:11], s[0:1]
	s_cbranch_execz .Lcc_skip_u4_7
	v_mov_b32_e32 v4, 0x6222000
	v_mov_b32_e32 v5, 0xe222000
	v_cndmask_b32_e32 v4, v4, v5, vcc
	v_mov_b32_e32 v5, v1
	v_lshl_add_u64 v[4:5], s[6:7], 0, v[4:5]
	v_lshl_add_u64 v[4:5], v[118:119], 2, v[4:5]
	v_add_co_u32_e32 v4, vcc, 0xffff8000, v4
	s_nop 1
	v_addc_co_u32_e32 v5, vcc, -1, v5, vcc
	s_nop 0
	global_store_dwordx4 v[4:5], v[48:51], off nt

; __device__ __forceinline__ void cache_convert(const Params& P, int l, int pct0, int pct1, int part, int nparts) {
;     int tid = threadIdx.x; asm volatile("" : "+v"(tid));
;     constexpr unsigned NGL = 32u * 512u * 512u / 8u;
;     const unsigned g0 = (unsigned)((unsigned long long)(2u * NGL) * pct0 / 100u), g1 = (unsigned)((unsigned long long)(2u * NGL) * pct1 / 100u);
;     const float* ck = P.in[3] + (size_t)l * 32 * 512 * 512; const float* cv = P.in[4] + (size_t)l * 32 * 512 * 512;
;     bf16_t* kb = (bf16_t*)(P.ws + WS_KB16) + (size_t)l * 32 * 512 * 512; bf16_t* vb = (bf16_t*)(P.ws + WS_VB16) + (size_t)l * 32 * 512 * 512;
;     float* ok = P.out + OFF_KS + (size_t)l * 32 * 512 * 512; float* ov = P.out + OFF_VS + (size_t)l * 32 * 512 * 512;
; #pragma unroll 8
;     for (unsigned gi = g0 + (unsigned)part * 512u + tid; gi < g1; gi += (unsigned)nparts * 512u) {
;         const bool isv = gi >= NGL; const unsigned e = (isv ? gi - NGL : gi) * 8u; const int key = (int)((e >> 9) & 511u);
;         const float* src = (isv ? cv : ck) + e;
;         const f32x4 k0 = *(const f32x4*)src, k1 = *(const f32x4*)(src + 4);
;         *(bf16x8*)((isv ? vb : kb) + e) = pack8v(k0, k1);
;         if (key >= 16) { float* d = (isv ? ov : ok) + e - 16 * 512; *(f32x4*)d = k0; *(f32x4*)(d + 4) = k1; }
;     }
.Lcc_try2:
	v_readlane_b32 s16, v10, 63
	s_mul_i32 s17, s13, 1
	s_add_u32 s16, s16, s17
	s_cmp_lt_u32 s16, s12
	s_cbranch_scc0 .Lcc_slow
	v_readlane_b32 s22, v253, 61
	v_readlane_b32 s23, v253, 62
	v_readlane_b32 s24, v253, 63
	v_readlane_b32 s25, v254, 0
	s_mov_b64 s[18:19], s[22:23]
	s_mov_b64 s[20:21], s[24:25]
	s_mov_b32 s0, 0xfffff
	s_mov_b32 s16, 0
	v_and_b32_e32 v2, 63, v208
	v_add_u32_e32 v3, 1, v2
	v_lshrrev_b32_e32 v3, 1, v3
	v_and_b32_e32 v2, 1, v2
	v_sub_u32_e32 v9, v10, v3
	v_lshlrev_b32_e32 v19, 2, v2
	v_mov_b32_e32 v105, 0
	v_mov_b32_e32 v107, 0
	v_mov_b32_e32 v109, 0
	v_mov_b32_e32 v111, 0
	v_add3_u32 v2, v9, s16, 0
	s_nop 0
	v_cmp_lt_u32_e32 vcc, s0, v2
	v_lshl_add_u32 v3, v2, 3, v19
	v_mov_b32_e32 v5, s19
	v_add_u32_e32 v4, 0xff800000, v3
	v_mov_b32_e32 v6, s21
	v_cndmask_b32_e32 v104, v3, v4, vcc
	v_cndmask_b32_e32 v7, v5, v6, vcc
	v_mov_b32_e32 v5, s18
	v_mov_b32_e32 v8, s20
	v_cndmask_b32_e32 v6, v5, v8, vcc
	v_lshl_add_u64 v[6:7], v[6:7], 0, s[62:63]
	v_lshl_add_u64 v[6:7], v[104:105], 2, v[6:7]
	global_load_dwordx4 v[20:23], v[6:7], off nt
	v_add3_u32 v2, v9, s16, 32
	s_nop 0
	v_cmp_lt_u32_e32 vcc, s0, v2
	v_lshl_add_u32 v3, v2, 3, v19
	v_mov_b32_e32 v5, s19
	v_add_u32_e32 v4, 0xff800000, v3
	v_mov_b32_e32 v6, s21
	v_cndmask_b32_e32 v106, v3, v4, vcc
	v_cndmask_b32_e32 v7, v5, v6, vcc
	v_mov_b32_e32 v5, s18
	v_mov_b32_e32 v8, s20
	v_cndmask_b32_e32 v6, v5, v8, vcc
	v_lshl_add_u64 v[6:7], v[6:7], 0, s[62:63]
	v_lshl_add_u64 v[6:7], v[106:107], 2, v[6:7]
	global_load_dwordx4 v[24:27], v[6:7], off nt
	s_add_u32 s16, s16, s13
	v_add3_u32 v2, v9, s16, 0
	s_nop 0
	v_cmp_lt_u32_e32 vcc, s0, v2
	v_lshl_add_u32 v3, v2, 3, v19
	v_mov_b32_e32 v5, s19
	v_add_u32_e32 v4, 0xff800000, v3
	v_mov_b32_e32 v6, s21
	v_cndmask_b32_e32 v108, v3, v4, vcc
	v_cndmask_b32_e32 v7, v5, v6, vcc
	v_mov_b32_e32 v5, s18
	v_mov_b32_e32 v8, s20
	v_cndmask_b32_e32 v6, v5, v8, vcc
	v_lshl_add_u64 v[6:7], v[6:7], 0, s[62:63]
	v_lshl_add_u64 v[6:7], v[108:109], 2, v[6:7]
	global_load_dwordx4 v[28:31], v[6:7], off nt
	v_add3_u32 v2, v9, s16, 32
	s_nop 0
	v_cmp_lt_u32_e32 vcc, s0, v2
	v_lshl_add_u32 v3, v2, 3, v19
	v_mov_b32_e32 v5, s19
	v_add_u32_e32 v4, 0xff800000, v3
	v_mov_b32_e32 v6, s21
	v_cndmask_b32_e32 v110, v3, v4, vcc
	v_cndmask_b32_e32 v7, v5, v6, vcc
	v_mov_b32_e32 v5, s18
	v_mov_b32_e32 v8, s20
	v_cndmask_b32_e32 v6, v5, v8, vcc
	v_lshl_add_u64 v[6:7], v[6:7], 0, s[62:63]
	v_lshl_add_u64 v[6:7], v[110:111], 2, v[6:7]
	global_load_dwordx4 v[32:35], v[6:7], off nt
	s_mov_b32 s16, 0
	v_add3_u32 v2, v9, s16, 0
	s_mov_b32 s0, 0xfffff
	v_mov_b32_e32 v4, 0x24300000
	v_cmp_lt_u32_e32 vcc, s0, v2
	v_mov_b32_e32 v5, 0x28300000
	v_mov_b32_e32 v17, v1
	v_and_b32_e32 v18, 0x3e000, v104
	v_cndmask_b32_e32 v16, v4, v5, vcc
	v_cmp_ne_u32_e64 s[0:1], 0, v18
	v_lshl_add_u64 v[16:17], s[4:5], 0, v[16:17]
	v_lshl_add_u64 v[16:17], v[104:105], 1, v[16:17]
	s_waitcnt vmcnt(3)
	v_cvt_pk_bf16_f32 v12, v20, v21
	v_cvt_pk_bf16_f32 v13, v22, v23
	s_nop 0
	global_store_dwordx2 v[16:17], v[12:13], off nt
	s_and_saveexec_b64 s[10:11], s[0:1]
	s_cbranch_execz .Lcc_skip_u2_0
	v_mov_b32_e32 v4, 0x6222000
	v_mov_b32_e32 v5, 0xe222000
	v_cndmask_b32_e32 v4, v4, v5, vcc
	v_mov_b32_e32 v5, v1
	v_lshl_add_u64 v[4:5], s[6:7], 0, v[4:5]
	v_lshl_add_u64 v[4:5], v[104:105], 2, v[4:5]
	v_add_co_u32_e32 v4, vcc, 0xffff8000, v4
	s_nop 1
	v_addc_co_u32_e32 v5, vcc, -1, v5, vcc
	s_nop 0
	global_store_dwordx4 v[4:5], v[20:23], off nt
.Lcc_skip_u2_0:
	s_or_b64 exec, exec, s[10:11]
	v_add3_u32 v2, v9, s16, 32
	s_mov_b32 s0, 0xfffff
	v_mov_b32_e32 v4, 0x24300000
	v_cmp_lt_u32_e32 vcc, s0, v2
	v_mov_b32_e32 v5, 0x28300000
	v_mov_b32_e32 v17, v1
	v_and_b32_e32 v18, 0x3e000, v106
	v_cndmask_b32_e32 v16, v4, v5, vcc
	v_cmp_ne_u32_e64 s[0:1], 0, v18
	v_lshl_add_u64 v[16:17], s[4:5], 0, v[16:17]
	v_lshl_add_u64 v[16:17], v[106:107], 1, v[16:17]
	s_waitcnt vmcnt(3)
	v_cvt_pk_bf16_f32 v14, v24, v25
	v_cvt_pk_bf16_f32 v15, v26, v27
	s_nop 0
	global_store_dwordx2 v[16:17], v[14:15], off nt
	s_and_saveexec_b64 s[10:11], s[0:1]
	s_cbranch_execz .Lcc_skip_u2_1
	v_mov_b32_e32 v4, 0x6222000
	v_mov_b32_e32 v5, 0xe222000
	v_cndmask_b32_e32 v4, v4, v5, vcc
	v_mov_b32_e32 v5, v1
	v_lshl_add_u64 v[4:5], s[6:7], 0, v[4:5]
	v_lshl_add_u64 v[4:5], v[106:107], 2, v[4:5]
	v_add_co_u32_e32 v4, vcc, 0xffff8000, v4
	s_nop 1
	v_addc_co_u32_e32 v5, vcc, -1, v5, vcc
	s_nop 0
	global_store_dwordx4 v[4:5], v[24:27], off nt
.Lcc_skip_u2_1:
	s_or_b64 exec, exec, s[10:11]
	s_add_u32 s16, s16, s13
	v_add3_u32 v2, v9, s16, 0
	s_mov_b32 s0, 0xfffff
	v_mov_b32_e32 v4, 0x24300000
	v_cmp_lt_u32_e32 vcc, s0, v2
	v_mov_b32_e32 v5, 0x28300000
	v_mov_b32_e32 v17, v1
	v_and_b32_e32 v18, 0x3e000, v108
	v_cndmask_b32_e32 v16, v4, v5, vcc
	v_cmp_ne_u32_e64 s[0:1], 0, v18
	v_lshl_add_u64 v[16:17], s[4:5], 0, v[16:17]
	v_lshl_add_u64 v[16:17], v[108:109], 1, v[16:17]
	s_waitcnt vmcnt(3)
	v_cvt_pk_bf16_f32 v100, v28, v29
	v_cvt_pk_bf16_f32 v101, v30, v31
	s_nop 0
	global_store_dwordx2 v[16:17], v[100:101], off nt
	s_and_saveexec_b64 s[10:11], s[0:1]
	s_cbranch_execz .Lcc_skip_u2_2
	v_mov_b32_e32 v4, 0x6222000
	v_mov_b32_e32 v5, 0xe222000
	v_cndmask_b32_e32 v4, v4, v5, vcc
	v_mov_b32_e32 v5, v1
	v_lshl_add_u64 v[4:5], s[6:7], 0, v[4:5]
	v_lshl_add_u64 v[4:5], v[108:109], 2, v[4:5]
	v_add_co_u32_e32 v4, vcc, 0xffff8000, v4
	s_nop 1
	v_addc_co_u32_e32 v5, vcc, -1, v5, vcc
	s_nop 0
	global_store_dwordx4 v[4:5], v[28:31], off nt
.Lcc_skip_u2_2:
	s_or_b64 exec, exec, s[10:11]
	v_add3_u32 v2, v9, s16, 32
	s_mov_b32 s0, 0xfffff
	v_mov_b32_e32 v4, 0x24300000
	v_cmp_lt_u32_e32 vcc, s0, v2
	v_mov_b32_e32 v5, 0x28300000
	v_mov_b32_e32 v17, v1
	v_and_b32_e32 v18, 0x3e000, v110
	v_cndmask_b32_e32 v16, v4, v5, vcc
	v_cmp_ne_u32_e64 s[0:1], 0, v18
	v_lshl_add_u64 v[16:17], s[4:5], 0, v[16:17]
	v_lshl_add_u64 v[16:17], v[110:111], 1, v[16:17]
	s_waitcnt vmcnt(3)
	v_cvt_pk_bf16_f32 v102, v32, v33
	v_cvt_pk_bf16_f32 v103, v34, v35
	s_nop 0
	global_store_dwordx2 v[16:17], v[102:103], off nt
	s_and_saveexec_b64 s[10:11], s[0:1]
	s_cbranch_execz .Lcc_skip_u2_3
	v_mov_b32_e32 v4, 0x6222000
	v_mov_b32_e32 v5, 0xe222000
	v_cndmask_b32_e32 v4, v4, v5, vcc
	v_mov_b32_e32 v5, v1
	v_lshl_add_u64 v[4:5], s[6:7], 0, v[4:5]
	v_lshl_add_u64 v[4:5], v[110:111], 2, v[4:5]
	v_add_co_u32_e32 v4, vcc, 0xffff8000, v4
	s_nop 1
	v_addc_co_u32_e32 v5, vcc, -1, v5, vcc
	s_nop 0
	global_store_dwordx4 v[4:5], v[32:35], off nt
